# GEMM K-loop: DMAs after MFMA 6/12/16/22
# baseline (speedup 1.0000x reference)
.LBB0_246:
	s_add_i32 s10, s7, 0xffffa000
	s_cmp_lg_u32 s7, 0
	s_cselect_b32 s12, s10, 0xc000
	v_add_u32_e32 v131, s7, v150
	s_waitcnt vmcnt(6)
	s_barrier
	v_add_u32_e32 v133, s7, v149
	ds_read_b128 v[154:157], v131 offset:0
	ds_read_b128 v[158:161], v131 offset:0x400
	ds_read_b128 v[162:165], v131 offset:0x800
	ds_read_b128 v[166:169], v131 offset:0xc00
	v_add_u32_e32 v131, s12, v147
	ds_read_b128 v[170:173], v133 offset:0
	ds_read_b128 v[174:177], v133 offset:0x400
	ds_read_b128 v[178:181], v133 offset:0x800
	ds_read_b128 v[200:203], v133 offset:0xc00
	ds_read_b128 v[204:207], v133 offset:0x1000
	ds_read_b128 v[208:211], v133 offset:0x1400
	ds_read_b128 v[212:215], v133 offset:0x1800
	ds_read_b128 v[216:219], v133 offset:0x1c00
	s_add_u32 s10, s8, s50
	s_addc_u32 s11, s9, s51
	v_readfirstlane_b32 s13, v131
	s_add_u32 s64, s5, s100
	s_addc_u32 s65, s6, 0
	s_sub_i32 s68, s13, s12
	s_lshr_b32 s68, s68, 1
	s_add_i32 s68, s68, s12
	s_addk_i32 s68, 0x4000
	s_mov_b32 m0, s13
	s_nop 0
	global_load_lds_dwordx4 v0, s[10:11]
	s_add_u32 m0, s13, 0x400
	s_nop 0
	global_load_lds_dwordx4 v130, s[10:11]
	s_waitcnt lgkmcnt(4)
	s_nop 0
	v_mfma_f32_16x16x32_bf16 v[126:129], v[154:157], v[170:173], v[126:129]
	v_mfma_f32_16x16x32_bf16 v[122:125], v[154:157], v[174:177], v[122:125]
	v_mfma_f32_16x16x32_bf16 v[118:121], v[154:157], v[178:181], v[118:121]
	v_mfma_f32_16x16x32_bf16 v[114:117], v[154:157], v[200:203], v[114:117]
	v_mfma_f32_16x16x32_bf16 v[110:113], v[158:161], v[170:173], v[110:113]
	v_mfma_f32_16x16x32_bf16 v[102:105], v[158:161], v[174:177], v[102:105]
	s_add_u32 m0, s13, 0x800
	s_nop 0
	global_load_lds_dwordx4 v132, s[10:11]
	v_mfma_f32_16x16x32_bf16 v[94:97], v[158:161], v[178:181], v[94:97]
	v_mfma_f32_16x16x32_bf16 v[86:89], v[158:161], v[200:203], v[86:89]
	v_mfma_f32_16x16x32_bf16 v[78:81], v[162:165], v[170:173], v[78:81]
	v_mfma_f32_16x16x32_bf16 v[70:73], v[162:165], v[174:177], v[70:73]
	v_mfma_f32_16x16x32_bf16 v[62:65], v[162:165], v[178:181], v[62:65]
	v_mfma_f32_16x16x32_bf16 v[54:57], v[162:165], v[200:203], v[54:57]
	s_add_u32 m0, s13, 0xc00
	s_nop 0
	global_load_lds_dwordx4 v136, s[10:11]
	v_mfma_f32_16x16x32_bf16 v[46:49], v[166:169], v[170:173], v[46:49]
	v_mfma_f32_16x16x32_bf16 v[38:41], v[166:169], v[174:177], v[38:41]
	v_mfma_f32_16x16x32_bf16 v[30:33], v[166:169], v[178:181], v[30:33]
	v_mfma_f32_16x16x32_bf16 v[22:25], v[166:169], v[200:203], v[22:25]
	s_mov_b32 m0, s68
	s_nop 0
	global_load_lds_dwordx4 v138, s[64:65]
	s_waitcnt lgkmcnt(0)
	s_nop 0
	v_mfma_f32_16x16x32_bf16 v[106:109], v[154:157], v[204:207], v[106:109]
	v_mfma_f32_16x16x32_bf16 v[98:101], v[154:157], v[208:211], v[98:101]
	v_mfma_f32_16x16x32_bf16 v[90:93], v[154:157], v[212:215], v[90:93]
	v_mfma_f32_16x16x32_bf16 v[82:85], v[154:157], v[216:219], v[82:85]
	v_mfma_f32_16x16x32_bf16 v[74:77], v[158:161], v[204:207], v[74:77]
	v_mfma_f32_16x16x32_bf16 v[66:69], v[158:161], v[208:211], v[66:69]
	s_add_u32 m0, s68, 0x400
	s_nop 0
	global_load_lds_dwordx4 v140, s[64:65]
	v_mfma_f32_16x16x32_bf16 v[58:61], v[158:161], v[212:215], v[58:61]
	v_mfma_f32_16x16x32_bf16 v[50:53], v[158:161], v[216:219], v[50:53]
	v_mfma_f32_16x16x32_bf16 v[42:45], v[162:165], v[204:207], v[42:45]
	v_mfma_f32_16x16x32_bf16 v[34:37], v[162:165], v[208:211], v[34:37]
	v_mfma_f32_16x16x32_bf16 v[26:29], v[162:165], v[212:215], v[26:29]
	v_mfma_f32_16x16x32_bf16 v[18:21], v[162:165], v[216:219], v[18:21]
	v_mfma_f32_16x16x32_bf16 v[14:17], v[166:169], v[204:207], v[14:17]
	v_mfma_f32_16x16x32_bf16 v[10:13], v[166:169], v[208:211], v[10:13]
	v_mfma_f32_16x16x32_bf16 v[6:9], v[166:169], v[212:215], v[6:9]
	v_mfma_f32_16x16x32_bf16 v[2:5], v[166:169], v[216:219], v[2:5]
	s_add_i32 s10, s7, 0x6000
	s_cmpk_lg_u32 s7, 0xc000
	s_cselect_b32 s7, s10, 0
	s_addk_i32 s100, 0x400
	s_add_u32 s50, s50, s60
	s_addc_u32 s51, s51, 0
	s_cmpk_lg_i32 s100, 0x7800
	s_cbranch_scc1 .LBB0_246
	s_waitcnt vmcnt(6)
	s_barrier
	v_add_u32_e32 v0, s7, v150
	v_add_u32_e32 v140, s7, v149
	ds_read_b128 v[130:133], v0 offset:0
	ds_read_b128 v[136:139], v0 offset:0x400
	ds_read_b128 v[154:157], v0 offset:0x800
	ds_read_b128 v[158:161], v0 offset:0xc00
	ds_read_b128 v[162:165], v140 offset:0
	ds_read_b128 v[166:169], v140 offset:0x400
	ds_read_b128 v[170:173], v140 offset:0x800
	ds_read_b128 v[174:177], v140 offset:0xc00
	ds_read_b128 v[178:181], v140 offset:0x1000
	ds_read_b128 v[200:203], v140 offset:0x1400
	ds_read_b128 v[204:207], v140 offset:0x1800
	ds_read_b128 v[208:211], v140 offset:0x1c00
	s_lshl_b32 s49, s4, 8
	s_waitcnt lgkmcnt(4)
	s_nop 0
	v_mfma_f32_16x16x32_bf16 v[126:129], v[130:133], v[162:165], v[126:129]
	v_mfma_f32_16x16x32_bf16 v[118:121], v[130:133], v[170:173], v[118:121]
	v_mfma_f32_16x16x32_bf16 v[114:117], v[130:133], v[174:177], v[114:117]
	v_mfma_f32_16x16x32_bf16 v[110:113], v[136:139], v[162:165], v[110:113]
	v_mfma_f32_16x16x32_bf16 v[102:105], v[136:139], v[166:169], v[102:105]
	v_mfma_f32_16x16x32_bf16 v[94:97], v[136:139], v[170:173], v[94:97]
	v_mfma_f32_16x16x32_bf16 v[86:89], v[136:139], v[174:177], v[86:89]
	v_mfma_f32_16x16x32_bf16 v[70:73], v[154:157], v[166:169], v[70:73]
	v_mfma_f32_16x16x32_bf16 v[62:65], v[154:157], v[170:173], v[62:65]
	v_mfma_f32_16x16x32_bf16 v[54:57], v[154:157], v[174:177], v[54:57]
	v_mfma_f32_16x16x32_bf16 v[46:49], v[158:161], v[162:165], v[46:49]
	v_mfma_f32_16x16x32_bf16 v[38:41], v[158:161], v[166:169], v[38:41]
	v_mfma_f32_16x16x32_bf16 v[30:33], v[158:161], v[170:173], v[30:33]
	v_mfma_f32_16x16x32_bf16 v[22:25], v[158:161], v[174:177], v[22:25]
	v_mfma_f32_16x16x32_bf16 v[212:215], v[130:133], v[166:169], v[122:125]
	v_mfma_f32_16x16x32_bf16 v[216:219], v[154:157], v[162:165], v[78:81]
	s_waitcnt lgkmcnt(0)
	s_nop 0
	v_mfma_f32_16x16x32_bf16 v[174:177], v[136:139], v[178:181], v[74:77]
	v_mfma_f32_16x16x32_bf16 v[220:223], v[136:139], v[200:203], v[66:69]
	v_mfma_f32_16x16x32_bf16 v[224:227], v[136:139], v[204:207], v[58:61]
	v_mfma_f32_16x16x32_bf16 v[50:53], v[136:139], v[208:211], v[50:53]
	v_mfma_f32_16x16x32_bf16 v[136:139], v[154:157], v[178:181], v[42:45]
	v_mfma_f32_16x16x32_bf16 v[34:37], v[154:157], v[200:203], v[34:37]
	v_mfma_f32_16x16x32_bf16 v[6:9], v[158:161], v[204:207], v[6:9]
	v_mfma_f32_16x16x32_bf16 v[162:165], v[130:133], v[178:181], v[106:109]
	v_mfma_f32_16x16x32_bf16 v[166:169], v[130:133], v[200:203], v[98:101]
	v_mfma_f32_16x16x32_bf16 v[170:173], v[130:133], v[204:207], v[90:93]
	v_mfma_f32_16x16x32_bf16 v[130:133], v[130:133], v[208:211], v[82:85]
	v_mfma_f32_16x16x32_bf16 v[228:231], v[154:157], v[204:207], v[26:29]
	v_mfma_f32_16x16x32_bf16 v[154:157], v[154:157], v[208:211], v[18:21]
	v_mfma_f32_16x16x32_bf16 v[178:181], v[158:161], v[178:181], v[14:17]
	v_mfma_f32_16x16x32_bf16 v[200:203], v[158:161], v[200:203], v[10:13]
	v_mfma_f32_16x16x32_bf16 v[158:161], v[158:161], v[208:211], v[2:5]
	s_waitcnt vmcnt(0)
	s_barrier
	ds_read_b128 v[2:5], v151 offset:0
	ds_read_b128 v[14:17], v151 offset:0x400
	ds_read_b128 v[204:207], v151 offset:0x800
	ds_read_b128 v[208:211], v151 offset:0xc00
	ds_read_b128 v[10:13], v152 offset:0
	ds_read_b128 v[18:21], v152 offset:0x400
	ds_read_b128 v[26:29], v152 offset:0x800
	ds_read_b128 v[42:45], v152 offset:0xc00
	ds_read_b128 v[232:235], v152 offset:0x1000
	ds_read_b128 v[236:239], v152 offset:0x1400
	ds_read_b128 v[240:243], v152 offset:0x1800
	ds_read_b128 v[244:247], v152 offset:0x1c00
	s_nop 0
	s_waitcnt lgkmcnt(4)
	s_nop 0
	v_mfma_f32_16x16x32_bf16 v[122:125], v[2:5], v[10:13], v[126:129]
	v_mfma_f32_16x16x32_bf16 v[106:109], v[2:5], v[18:21], v[212:215]
	v_mfma_f32_16x16x32_bf16 v[90:93], v[2:5], v[26:29], v[118:121]
	v_mfma_f32_16x16x32_bf16 v[74:77], v[2:5], v[42:45], v[114:117]
	v_mfma_f32_16x16x32_bf16 v[126:129], v[14:17], v[10:13], v[110:113]
	v_mfma_f32_16x16x32_bf16 v[110:113], v[14:17], v[18:21], v[102:105]
	v_mfma_f32_16x16x32_bf16 v[94:97], v[14:17], v[26:29], v[94:97]
	v_mfma_f32_16x16x32_bf16 v[78:81], v[14:17], v[42:45], v[86:89]
	v_mfma_f32_16x16x32_bf16 v[114:117], v[204:207], v[10:13], v[216:219]
	v_mfma_f32_16x16x32_bf16 v[98:101], v[204:207], v[18:21], v[70:73]
	v_mfma_f32_16x16x32_bf16 v[82:85], v[204:207], v[26:29], v[62:65]
	v_mfma_f32_16x16x32_bf16 v[66:69], v[204:207], v[42:45], v[54:57]
	v_mfma_f32_16x16x32_bf16 v[118:121], v[208:211], v[10:13], v[46:49]
	v_mfma_f32_16x16x32_bf16 v[102:105], v[208:211], v[18:21], v[38:41]
	v_mfma_f32_16x16x32_bf16 v[86:89], v[208:211], v[26:29], v[30:33]
	v_mfma_f32_16x16x32_bf16 v[70:73], v[208:211], v[42:45], v[22:25]
	s_waitcnt lgkmcnt(0)
	s_nop 0
	v_mfma_f32_16x16x32_bf16 v[58:61], v[2:5], v[232:235], v[162:165]
	v_mfma_f32_16x16x32_bf16 v[42:45], v[2:5], v[236:239], v[166:169]
	v_mfma_f32_16x16x32_bf16 v[26:29], v[2:5], v[240:243], v[170:173]
	v_mfma_f32_16x16x32_bf16 v[10:13], v[2:5], v[244:247], v[130:133]
	v_mfma_f32_16x16x32_bf16 v[62:65], v[14:17], v[232:235], v[174:177]
	v_mfma_f32_16x16x32_bf16 v[46:49], v[14:17], v[236:239], v[220:223]
	v_mfma_f32_16x16x32_bf16 v[30:33], v[14:17], v[240:243], v[224:227]
	v_mfma_f32_16x16x32_bf16 v[14:17], v[14:17], v[244:247], v[50:53]
	v_mfma_f32_16x16x32_bf16 v[50:53], v[204:207], v[232:235], v[136:139]
	v_mfma_f32_16x16x32_bf16 v[34:37], v[204:207], v[236:239], v[34:37]
	v_mfma_f32_16x16x32_bf16 v[18:21], v[204:207], v[240:243], v[228:231]
	v_mfma_f32_16x16x32_bf16 v[2:5], v[204:207], v[244:247], v[154:157]
	v_mfma_f32_16x16x32_bf16 v[54:57], v[208:211], v[232:235], v[178:181]
	v_mfma_f32_16x16x32_bf16 v[38:41], v[208:211], v[236:239], v[200:203]
	v_mfma_f32_16x16x32_bf16 v[22:25], v[208:211], v[240:243], v[6:9]
	v_mfma_f32_16x16x32_bf16 v[6:9], v[208:211], v[244:247], v[158:161]
	v_mov_b32_e32 v136, v134
	s_mov_b64 s[50:51], -1
	s_and_b64 vcc, exec, s[22:23]
	s_barrier
	s_cbranch_vccz .LBB0_264
	s_and_b64 vcc, exec, s[0:1]
	s_cbranch_vccz .LBB0_250
	v_lshrrev_b32_e32 v0, 6, v136
	v_mul_lo_u32 v137, v0, s14
	v_and_b32_e32 v130, 15, v136
	v_and_or_b32 v0, v136, 48, v137
	s_movk_i32 s4, 0x90
	v_mad_u32_u24 v0, v130, s4, v0
	v_cvt_pk_bf16_f32 v130, v122, v123
	v_cvt_pk_bf16_f32 v131, v124, v125
	v_cvt_pk_bf16_f32 v132, v126, v127
	v_cvt_pk_bf16_f32 v133, v128, v129
	s_waitcnt vmcnt(0)
	ds_write_b128 v0, v[130:133]
	v_cvt_pk_bf16_f32 v130, v114, v115
	v_cvt_pk_bf16_f32 v131, v116, v117
	v_cvt_pk_bf16_f32 v132, v118, v119
	v_cvt_pk_bf16_f32 v133, v120, v121
	ds_write_b128 v0, v[130:133] offset:64
	v_cvt_pk_bf16_f32 v130, v106, v107
	v_cvt_pk_bf16_f32 v131, v108, v109
	v_cvt_pk_bf16_f32 v132, v110, v111
	v_cvt_pk_bf16_f32 v133, v112, v113
	ds_write_b128 v0, v[130:133] offset:2304
	v_cvt_pk_bf16_f32 v130, v98, v99
	v_cvt_pk_bf16_f32 v131, v100, v101
	v_cvt_pk_bf16_f32 v132, v102, v103
	v_cvt_pk_bf16_f32 v133, v104, v105
	ds_write_b128 v0, v[130:133] offset:2368
	v_cvt_pk_bf16_f32 v130, v90, v91
	v_cvt_pk_bf16_f32 v131, v92, v93
	v_cvt_pk_bf16_f32 v132, v94, v95
	v_cvt_pk_bf16_f32 v133, v96, v97
	ds_write_b128 v0, v[130:133] offset:4608
	v_cvt_pk_bf16_f32 v130, v82, v83
	v_cvt_pk_bf16_f32 v131, v84, v85
	v_cvt_pk_bf16_f32 v132, v86, v87
	v_cvt_pk_bf16_f32 v133, v88, v89
	ds_write_b128 v0, v[130:133] offset:4672
	v_cvt_pk_bf16_f32 v130, v74, v75
	v_cvt_pk_bf16_f32 v131, v76, v77
	v_cvt_pk_bf16_f32 v132, v78, v79
	v_cvt_pk_bf16_f32 v133, v80, v81
	ds_write_b128 v0, v[130:133] offset:6912
	v_cvt_pk_bf16_f32 v130, v66, v67
	v_cvt_pk_bf16_f32 v131, v68, v69
	v_cvt_pk_bf16_f32 v132, v70, v71
	v_cvt_pk_bf16_f32 v133, v72, v73
	ds_write_b128 v0, v[130:133] offset:6976
	v_cvt_pk_bf16_f32 v130, v58, v59
	v_cvt_pk_bf16_f32 v131, v60, v61
	v_cvt_pk_bf16_f32 v132, v62, v63
	v_cvt_pk_bf16_f32 v133, v64, v65
	ds_write_b128 v0, v[130:133] offset:9216
	v_cvt_pk_bf16_f32 v130, v50, v51
	v_cvt_pk_bf16_f32 v131, v52, v53
	v_cvt_pk_bf16_f32 v132, v54, v55
	v_cvt_pk_bf16_f32 v133, v56, v57
	ds_write_b128 v0, v[130:133] offset:9280
	v_cvt_pk_bf16_f32 v130, v42, v43
	v_cvt_pk_bf16_f32 v131, v44, v45
	v_cvt_pk_bf16_f32 v132, v46, v47
	v_cvt_pk_bf16_f32 v133, v48, v49
	ds_write_b128 v0, v[130:133] offset:11520
	v_cvt_pk_bf16_f32 v130, v34, v35
	v_cvt_pk_bf16_f32 v131, v36, v37
	v_cvt_pk_bf16_f32 v132, v38, v39
	v_cvt_pk_bf16_f32 v133, v40, v41
	ds_write_b128 v0, v[130:133] offset:11584
	v_cvt_pk_bf16_f32 v130, v26, v27
	v_cvt_pk_bf16_f32 v131, v28, v29
	v_cvt_pk_bf16_f32 v132, v30, v31
	v_cvt_pk_bf16_f32 v133, v32, v33
	ds_write_b128 v0, v[130:133] offset:13824
	v_cvt_pk_bf16_f32 v130, v18, v19
	v_cvt_pk_bf16_f32 v131, v20, v21
	v_cvt_pk_bf16_f32 v132, v22, v23
	v_cvt_pk_bf16_f32 v133, v24, v25
	ds_write_b128 v0, v[130:133] offset:13888
	v_cvt_pk_bf16_f32 v130, v10, v11
	v_cvt_pk_bf16_f32 v131, v12, v13
	v_cvt_pk_bf16_f32 v132, v14, v15
	v_cvt_pk_bf16_f32 v133, v16, v17
	ds_write_b128 v0, v[130:133] offset:16128
	v_cvt_pk_bf16_f32 v130, v2, v3
	v_cvt_pk_bf16_f32 v131, v4, v5
	v_cvt_pk_bf16_f32 v132, v6, v7
	v_cvt_pk_bf16_f32 v133, v8, v9
	ds_write_b128 v0, v[130:133] offset:16192
	v_and_b32_e32 v0, 0xffffff80, v136
	v_add_u32_e32 v130, s48, v0
	v_ashrrev_i32_e32 v131, 31, v130
	v_lshlrev_b64 v[130:131], 11, v[130:131]
	v_lshl_add_u64 v[130:131], s[38:39], 0, v[130:131]
	v_and_b32_e32 v0, 64, v136
	v_lshl_add_u64 v[130:131], s[46:47], 1, v[130:131]
	v_lshlrev_b32_e32 v0, 1, v0
	v_lshl_add_u64 v[138:139], v[130:131], 0, v[0:1]
	v_lshlrev_b32_e32 v0, 4, v136
	v_and_b32_e32 v0, 0x70, v0
	v_bfe_u32 v140, v136, 3, 3
	v_or_b32_e32 v130, v137, v0
	s_waitcnt lgkmcnt(0)
	v_mad_u32_u24 v137, v140, s4, v130
	ds_read_b128 v[130:133], v137
	v_lshl_add_u64 v[138:139], v[138:139], 0, v[0:1]
	v_lshlrev_b32_e32 v0, 11, v140
	v_lshl_add_u64 v[140:141], v[138:139], 0, v[0:1]
	s_mov_b64 s[50:51], 0
	s_waitcnt lgkmcnt(0)
	global_store_dwordx4 v[140:141], v[130:133], off
	ds_read_b128 v[130:133], v137 offset:1152
	v_or_b32_e32 v140, 0x4000, v0
	v_mov_b32_e32 v141, v1
	v_lshl_add_u64 v[140:141], v[138:139], 0, v[140:141]
	s_waitcnt lgkmcnt(0)
	global_store_dwordx4 v[140:141], v[130:133], off
	ds_read_b128 v[130:133], v137 offset:2304
	v_or_b32_e32 v140, 0x8000, v0
	v_mov_b32_e32 v141, v1
	v_lshl_add_u64 v[140:141], v[138:139], 0, v[140:141]
	s_waitcnt lgkmcnt(0)
	global_store_dwordx4 v[140:141], v[130:133], off
	ds_read_b128 v[130:133], v137 offset:3456
	v_or_b32_e32 v140, 0xc000, v0
	v_mov_b32_e32 v141, v1
	v_lshl_add_u64 v[140:141], v[138:139], 0, v[140:141]
	s_waitcnt lgkmcnt(0)
	global_store_dwordx4 v[140:141], v[130:133], off
	ds_read_b128 v[130:133], v137 offset:4608
	v_or_b32_e32 v140, 0x10000, v0
	v_mov_b32_e32 v141, v1
	v_lshl_add_u64 v[140:141], v[138:139], 0, v[140:141]
	s_waitcnt lgkmcnt(0)
	global_store_dwordx4 v[140:141], v[130:133], off
	ds_read_b128 v[130:133], v137 offset:5760
	v_or_b32_e32 v140, 0x14000, v0
	v_mov_b32_e32 v141, v1
	v_lshl_add_u64 v[140:141], v[138:139], 0, v[140:141]
	s_waitcnt lgkmcnt(0)
	global_store_dwordx4 v[140:141], v[130:133], off
	ds_read_b128 v[130:133], v137 offset:6912
	v_or_b32_e32 v140, 0x18000, v0
	v_mov_b32_e32 v141, v1
	v_lshl_add_u64 v[140:141], v[138:139], 0, v[140:141]
	s_waitcnt lgkmcnt(0)
	global_store_dwordx4 v[140:141], v[130:133], off
	ds_read_b128 v[130:133], v137 offset:8064
	v_or_b32_e32 v140, 0x1c000, v0
	v_mov_b32_e32 v141, v1
	v_lshl_add_u64 v[140:141], v[138:139], 0, v[140:141]
	s_waitcnt lgkmcnt(0)
	global_store_dwordx4 v[140:141], v[130:133], off
	ds_read_b128 v[130:133], v137 offset:9216
	v_or_b32_e32 v140, 0x20000, v0
	v_mov_b32_e32 v141, v1
	v_lshl_add_u64 v[140:141], v[138:139], 0, v[140:141]
	s_waitcnt lgkmcnt(0)
	global_store_dwordx4 v[140:141], v[130:133], off
	ds_read_b128 v[130:133], v137 offset:10368
	v_or_b32_e32 v140, 0x24000, v0
	v_mov_b32_e32 v141, v1
	v_lshl_add_u64 v[140:141], v[138:139], 0, v[140:141]
	s_waitcnt lgkmcnt(0)
	global_store_dwordx4 v[140:141], v[130:133], off
	ds_read_b128 v[130:133], v137 offset:11520
	v_or_b32_e32 v140, 0x28000, v0
	v_mov_b32_e32 v141, v1
	v_lshl_add_u64 v[140:141], v[138:139], 0, v[140:141]
	s_waitcnt lgkmcnt(0)
	global_store_dwordx4 v[140:141], v[130:133], off
	ds_read_b128 v[130:133], v137 offset:12672
	v_or_b32_e32 v140, 0x2c000, v0
	v_mov_b32_e32 v141, v1
	v_lshl_add_u64 v[140:141], v[138:139], 0, v[140:141]
	s_waitcnt lgkmcnt(0)
	global_store_dwordx4 v[140:141], v[130:133], off
	ds_read_b128 v[130:133], v137 offset:13824
	v_or_b32_e32 v140, 0x30000, v0
	v_mov_b32_e32 v141, v1
	v_lshl_add_u64 v[140:141], v[138:139], 0, v[140:141]
	s_waitcnt lgkmcnt(0)
	global_store_dwordx4 v[140:141], v[130:133], off
	ds_read_b128 v[130:133], v137 offset:14976
	v_or_b32_e32 v140, 0x34000, v0
	v_mov_b32_e32 v141, v1
	v_lshl_add_u64 v[140:141], v[138:139], 0, v[140:141]
	s_waitcnt lgkmcnt(0)
	global_store_dwordx4 v[140:141], v[130:133], off
	ds_read_b128 v[130:133], v137 offset:16128
	v_or_b32_e32 v140, 0x38000, v0
	v_mov_b32_e32 v141, v1
	v_lshl_add_u64 v[140:141], v[138:139], 0, v[140:141]
	v_or_b32_e32 v0, 0x3c000, v0
	s_waitcnt lgkmcnt(0)
	global_store_dwordx4 v[140:141], v[130:133], off
	ds_read_b128 v[130:133], v137 offset:17280
	v_lshl_add_u64 v[138:139], v[138:139], 0, v[0:1]
	s_waitcnt lgkmcnt(0)
	global_store_dwordx4 v[138:139], v[130:133], off
	s_waitcnt lgkmcnt(0)
	s_barrier
